# S3 work queue: next item index claimed one item ahead (atomic latency hidden behind the current item)
# baseline (speedup 1.0000x reference)
; #define LAS __attribute__((address_space(3)))
; DEV void attn_item(const Fr& F, int l, int b, int qb, int kvh, bool ctxq) {
;     ...
;         for (int ks = 0; ks < 2; ++ks) { const int t = r0 + 16 * mt + fr; float x[8];
;             load_rope8(F, F.Z + (size_t)(qrow0 + t) * ZS + ZC_AQ + (kvh * 2 + g) * 64, 32 * ks + 8 * fq, qb * 128 + t, !ctxq, x);
; #pragma unroll
;             for (int e = 0; e < 8; ++e) x[e] *= 0.18033688011f;
;             xq[mt][ks] = pack8(x); }
;     const float sink = F.in[I_SINK][l * 4 + kvh * 2 + g] * 1.44269504089f;
;     float mrow[2], lrow[2]; f32x4 O[2][4];
; #pragma unroll
;     for (int mt = 0; mt < 2; ++mt) { mrow[mt] = sink; lrow[mt] = 1.f;
; #pragma unroll
;         for (int n = 0; n < 4; ++n) O[mt][n] = (f32x4){0.f, 0.f, 0.f, 0.f}; }
;     LAS bf16_t* Pw = Ps + w * 32 * 136;
;     const int ktl[5] = {0, 1, 2, 3, 4};
;     int kt = 0; const int nkt = ctxq ? 2 : 5;
;     u32x4 rk[2], rp[2], rv[2];
;     auto tile_ok = [&](int k) { const int kb = qb + k - 3; return k < 2 || (kb >= 0 && kb < SEQ / 128); };
;     ...
;     (void)ktl;
;     while (kt < nkt && !tile_ok(kt)) ++kt;
;     if (kt < nkt) ATT_PREFETCH(kt);
;     while (kt < nkt) {
;         const int kb = qb + kt - 3; const bool rope = kt >= 2;
;         __syncthreads();
; #pragma unroll
;         for (int i = 0; i < 2; ++i) { const int idx = tid + NTHR * i; const int s_ = idx >> 3, c8 = (idx & 7) * 8;
;             float x[8]; unpack8(rk[i], x);
;             if (rope) { float pr[8]; unpack8(rp[i], pr); const bool second = (c8 & 16) != 0; const int n = kb * 128 + s_;
;                 const int pos = (c8 >= 32) ? (n & 63) : (n >> 6); const float* tb = F.ROPE + (size_t)(pos * 16 + (c8 & 8)) * 2;
; #pragma unroll
;                 for (int e = 0; e < 8; ++e) { const float c = tb[2 * e], sn = tb[2 * e + 1]; x[e] = second ? (x[e] * c + pr[e] * sn) : (x[e] * c - pr[e] * sn); } }
;             *(LAS bf16x8*)(Ks + s_ * 72 + c8) = pack8(x);
;             *(LAS u32x4*)(Vs + s_ * 72 + c8) = rv[i]; }
;         __syncthreads();
;         int kn = kt + 1; while (kn < nkt && !tile_ok(kn)) ++kn;
;         if (kn < nkt) ATT_PREFETCH(kn);
;         const int nlo = (kt == 2) ? 2 * rq : 0, nhi = (kt == 4) ? 2 * rq + 2 : 8;
;         f32x4 sc[2][8];
; #pragma unroll
;         for (int nt = 0; nt < 8; ++nt) { if (nt >= nlo && nt < nhi) {
.LBB0_473:
	s_mov_b32 s67, 0xff800000
	s_movk_i32 s66, 0x1400
	s_or_b64 exec, exec, s[2:3]
	s_lshl_b32 s0, s24, 4
	v_mov_b32_e32 v12, v188
	s_mov_b32 s4, s0
	s_mov_b32 s1, s61
	v_readfirstlane_b32 s2, v12
	v_writelane_b32 v239, s4, 50
	s_ashr_i32 s3, s2, 6
	s_lshl_b64 s[0:1], s[0:1], 2
	v_writelane_b32 v239, s5, 51
	v_readlane_b32 s4, v241, 61
	s_add_u32 s4, s4, s0
	v_readlane_b32 s0, v241, 62
	s_addc_u32 s5, s0, s1
	v_writelane_b32 v239, s4, 52
	s_lshl_b32 s0, s24, 16
	s_lshl_b32 s60, s24, 8
	v_writelane_b32 v239, s5, 53
	v_writelane_b32 v239, s0, 54
	s_lshl_b32 s0, s24, 2
	v_writelane_b32 v239, s0, 55
	v_cmp_eq_u32_e64 s[0:1], 0, v12
	s_waitcnt vmcnt(9)
	v_lshlrev_b32_e32 v20, 3, v12
	v_add_u32_e32 v4, 0x200, v12
	v_writelane_b32 v239, s0, 57
	s_movk_i32 s24, 0x90
	v_lshrrev_b32_e32 v8, 4, v12
	v_writelane_b32 v239, s1, 58
	s_movk_i32 s0, 0x480
	v_cmp_gt_i32_e64 s[0:1], s0, v12
	v_and_b32_e32 v150, 56, v20
	v_ashrrev_i32_e32 v151, 3, v4
	v_writelane_b32 v239, s0, 59
	v_mul_lo_u32 v18, v8, s24
	v_lshrrev_b32_e32 v8, 4, v4
	v_writelane_b32 v239, s1, 60
	s_movk_i32 s0, 0x280
	v_cmp_gt_i32_e64 s[0:1], s0, v12
	v_lshlrev_b32_e32 v154, 2, v4
	v_lshlrev_b32_e32 v4, 5, v4
	v_writelane_b32 v239, s0, 61
	v_readlane_b32 s16, v242, 0
	v_add_u32_e32 v6, 0x400, v12
	v_writelane_b32 v239, s1, 62
	s_movk_i32 s0, 0x80
	v_cmp_gt_i32_e64 s[0:1], s0, v12
	v_lshl_add_u32 v7, v150, 2, 0
	v_and_b32_e32 v4, 0xffffff00, v4
	v_writelane_b32 v239, s0, 63
	v_readlane_b32 s17, v242, 1
	v_add_u32_e32 v199, v7, v4
	v_writelane_b32 v237, s1, 0
	v_lshlrev_b32_e32 v4, 5, v6
	s_lshl_b64 s[4:5], s[60:61], 2
	s_mov_b64 s[0:1], s[16:17]
	v_and_b32_e32 v4, 0xffffff00, v4
	s_add_u32 s38, s0, s4
	v_ashrrev_i32_e32 v184, 3, v6
	v_add_u32_e32 v200, v7, v4
	v_bfe_u32 v4, v12, 2, 2
	v_lshrrev_b32_e32 v6, 1, v12
	v_writelane_b32 v237, s4, 1
	s_addc_u32 s39, s1, s5
	s_and_b32 s6, s3, 3
	v_mul_lo_u32 v19, v8, s24
	v_lshlrev_b32_e32 v8, 5, v12
	v_and_or_b32 v4, v6, 24, v4
	v_writelane_b32 v237, s5, 2
	v_bfe_u32 v21, v12, 4, 2
	s_lshl_b32 s1, s6, 5
	v_and_b32_e32 v15, 15, v12
	v_and_b32_e32 v8, 0xffffff00, v8
	v_mul_u32_u24_e32 v202, 0x90, v4
	s_ashr_i32 s0, s2, 8
	v_writelane_b32 v237, s1, 3
	v_lshlrev_b32_e32 v4, 3, v21
	v_lshlrev_b32_e32 v152, 2, v12
	v_add_u32_e32 v198, v7, v8
	v_and_b32_e32 v6, 24, v20
	v_or_b32_e32 v203, s1, v15
	v_writelane_b32 v237, s0, 5
	s_lshl_b32 s0, s0, 6
	v_and_b32_e32 v8, 32, v12
	v_or_b32_e32 v10, 32, v4
	v_add_u32_e32 v201, 0, v6
	v_writelane_b32 v237, s0, 7
	v_cmp_eq_u32_e64 s[46:47], 0, v8
	v_and_b32_e32 v204, 64, v152
	v_sub_u32_e32 v6, v4, v8
	v_sub_u32_e32 v8, v10, v8
	v_lshlrev_b32_e32 v10, 7, v203
	s_movk_i32 s0, 0x1780
	v_readlane_b32 s4, v242, 28
	v_and_or_b32 v10, v10, s0, v204
	v_mov_b32_e32 v11, v0
	v_readlane_b32 s5, v242, 29
	v_or_b32_e32 v205, 16, v203
	v_and_b32_e32 v2, 3, v12
	v_lshl_add_u64 v[156:157], s[4:5], 0, v[10:11]
	v_lshlrev_b32_e32 v10, 7, v205
	s_movk_i32 s0, 0x1f80
	v_ashrrev_i32_e32 v185, 2, v12
	v_lshlrev_b32_e32 v5, 6, v2
	v_and_or_b32 v10, v10, s0, v204
	v_add_u32_e32 v3, 0, v5
	v_lshlrev_b32_e32 v13, 8, v185
	v_lshlrev_b32_e32 v2, 5, v2
	v_lshl_or_b32 v187, s3, 4, v15
	v_lshl_add_u64 v[158:159], s[4:5], 0, v[10:11]
	s_mulk_i32 s3, 0x2200
	v_and_b32_e32 v10, 2, v12
	v_lshlrev_b32_e32 v14, 1, v150
	v_ashrrev_i32_e32 v141, 3, v12
	v_add_u32_e32 v186, v3, v13
	v_sub_u32_e32 v3, v3, v2
	v_mul_lo_u32 v2, v187, s24
	v_and_b32_e32 v17, 48, v12
	s_add_i32 s0, s3, 0
	v_bfe_i32 v11, v12, 1, 1
	v_cmp_eq_u32_e64 s[48:49], 0, v10
	v_add_u32_e32 v10, 0, v14
	s_waitcnt vmcnt(8)
	v_mul_u32_u24_e32 v23, 0x110, v15
	v_add_u32_e32 v16, 0, v2
	v_lshrrev_b32_e32 v2, 2, v12
	v_lshlrev_b32_e32 v12, 2, v21
	v_add_u32_e32 v22, s0, v4
	v_add3_u32 v207, s0, v23, v17
	v_mad_u64_u32 v[160:161], s[0:1], v141, s24, v[10:11]
	v_mad_u64_u32 v[162:163], s[0:1], v151, s24, v[10:11]
	v_mul_u32_u24_e32 v10, 0x90, v15
	v_add3_u32 v163, 0, v10, v17
	v_or_b32_e32 v10, 1, v12
	v_cmp_ge_u32_e64 s[0:1], v10, v203
	v_or_b32_e32 v10, 2, v12
	s_lshl_b32 s15, s6, 1
	v_writelane_b32 v237, s0, 9
	s_add_i32 s33, s15, 2
	s_cmp_eq_u32 s6, 0
	v_writelane_b32 v237, s1, 10
	v_cmp_lt_u32_e64 s[0:1], v12, v203
	s_cselect_b64 s[2:3], -1, 0
	s_cmp_lg_u32 s6, 0
	v_writelane_b32 v237, s0, 11
	s_cselect_b64 s[4:5], -1, 0
	s_cmp_lg_u32 s6, 1
	v_writelane_b32 v237, s1, 12
	v_cmp_ge_u32_e64 s[0:1], v10, v203
	v_readlane_b32 s18, v242, 2
	v_readlane_b32 s19, v242, 3
	v_writelane_b32 v237, s0, 13
	s_cselect_b64 s[16:17], -1, 0
	s_cmp_gt_u32 s6, 1
	v_writelane_b32 v237, s1, 14
	v_cmp_le_u32_e64 s[0:1], v10, v203
	v_or_b32_e32 v10, 3, v12
	v_readlane_b32 s20, v242, 4
	v_writelane_b32 v237, s0, 15
	v_readlane_b32 s21, v242, 5
	s_cselect_b64 s[18:19], -1, 0
	v_writelane_b32 v237, s1, 16
	v_cmp_ge_u32_e64 s[0:1], v10, v203
	s_cmp_lt_u32 s6, 2
	s_cselect_b64 s[20:21], -1, 0
	v_writelane_b32 v237, s0, 17
	s_cmp_lg_u32 s6, 2
	s_cselect_b64 s[36:37], -1, 0
	v_writelane_b32 v237, s1, 18
	v_cmp_le_u32_e64 s[0:1], v10, v203
	v_or_b32_e32 v10, 32, v12
	s_cmp_eq_u32 s6, 3
	v_writelane_b32 v237, s0, 19
	v_readlane_b32 s22, v242, 6
	v_readlane_b32 s23, v242, 7
	v_writelane_b32 v237, s1, 20
	v_cmp_ge_u32_e64 s[0:1], v10, v203
	v_mul_lo_u32 v9, v185, s24
	v_and_b32_e32 v1, 0x78, v20
	v_writelane_b32 v237, s0, 21
	v_and_b32_e32 v2, 12, v2
	v_mov_b32_e32 v15, v0
	v_writelane_b32 v237, s1, 22
	v_cmp_le_u32_e64 s[0:1], v10, v203
	v_or_b32_e32 v10, 33, v12
	v_add_u32_e32 v1, 0, v1
	v_writelane_b32 v237, s0, 23
	v_ashrrev_i32_e32 v7, 31, v6
	v_and_b32_e32 v206, 8, v20
	v_writelane_b32 v237, s1, 24
	v_cmp_ge_u32_e64 s[0:1], v10, v203
	v_lshlrev_b32_e32 v20, 2, v2
	v_mov_b32_e32 v21, v0
	v_writelane_b32 v237, s0, 25
; DEV void attn_item(const Fr& F, int l, int b, int qb, int kvh, bool ctxq) {
;     ...
;             const int tl = r0 + mt * 16 + fr;
;             float mx = -INFINITY;
; #pragma unroll
;             for (int nt = 0; nt < 8; ++nt) { if (nt >= nlo && nt < nhi) {
;                 const bool dg = (kt == 2 || kt == 4) && (nt == 2 * rq + mt);
;                 if (dg) {
; #pragma unroll
;                     for (int j = 0; j < 4; ++j) { const int si = nt * 16 + 4 * fq + j; const bool ok = (kt == 2) ? (si >= tl) : (si <= tl); sc[mt][nt][j] = ok ? sc[mt][nt][j] : -INFINITY; } }
;                 else if ((kt == 2 && nt < 2 * rq + mt) || (kt == 4 && nt > 2 * rq + mt)) sc[mt][nt] = (f32x4){-INFINITY, -INFINITY, -INFINITY, -INFINITY};
	v_or_b32_e32 v5, v13, v5
	v_ashrrev_i32_e32 v153, 31, v152
	v_writelane_b32 v237, s1, 26
	v_cmp_le_u32_e64 s[0:1], v10, v203
	v_or_b32_e32 v10, 34, v12
	v_ashrrev_i32_e32 v155, 31, v154
	v_writelane_b32 v237, s0, 27
	v_cmp_lt_u32_e64 s[50:51], 31, v150
	v_and_b32_e32 v208, 63, v141
	v_writelane_b32 v237, s1, 28
	v_cmp_ge_u32_e64 s[0:1], v10, v203
	v_and_b32_e32 v161, 63, v151
	v_cmp_ge_u32_e64 s[52:53], v12, v203
	v_writelane_b32 v237, s0, 29
	v_cmp_le_u32_e64 s[54:55], v12, v203
	v_add_u32_e32 v210, v1, v18
	v_writelane_b32 v237, s1, 30
	v_cmp_le_u32_e64 s[0:1], v10, v203
	v_or_b32_e32 v10, 35, v12
	v_add_u32_e32 v211, v1, v19
	v_writelane_b32 v237, s0, 31
	v_add_u32_e32 v212, v3, v9
	v_add_u32_e32 v213, v16, v17
	v_writelane_b32 v237, s1, 32
	v_cmp_ge_u32_e64 s[0:1], v10, v203
	v_lshlrev_b32_e32 v168, 1, v2
	v_lshlrev_b32_e32 v170, 1, v4
	v_writelane_b32 v237, s0, 33
	v_lshlrev_b64 v[172:173], 1, v[6:7]
	v_lshlrev_b32_e32 v174, 1, v8
	v_writelane_b32 v237, s1, 34
	v_cmp_le_u32_e64 s[0:1], v10, v203
	v_or_b32_e32 v10, 64, v12
	v_lshlrev_b32_e32 v176, 1, v12
	v_writelane_b32 v237, s0, 35
	v_add_u32_e32 v214, v22, v23
	s_nop 0
	v_writelane_b32 v237, s1, 36
	v_cmp_ge_u32_e64 s[0:1], v10, v203
	s_nop 1
	v_writelane_b32 v237, s0, 37
	s_nop 1
	v_writelane_b32 v237, s1, 38
	v_cmp_le_u32_e64 s[0:1], v10, v203
	v_or_b32_e32 v10, 0x41, v12
	s_nop 0
	v_writelane_b32 v237, s0, 39
	s_nop 1
	v_writelane_b32 v237, s1, 40
	v_cmp_ge_u32_e64 s[0:1], v10, v203
	s_nop 1
	v_writelane_b32 v237, s0, 41
	s_nop 1
	v_writelane_b32 v237, s1, 42
	v_cmp_le_u32_e64 s[0:1], v10, v203
	v_or_b32_e32 v10, 0x42, v12
	s_nop 0
	v_writelane_b32 v237, s0, 43
	s_nop 1
	v_writelane_b32 v237, s1, 44
	v_cmp_ge_u32_e64 s[0:1], v10, v203
	s_nop 1
	v_writelane_b32 v237, s0, 45
	s_nop 1
	v_writelane_b32 v237, s1, 46
	v_cmp_le_u32_e64 s[0:1], v10, v203
	v_or_b32_e32 v10, 0x43, v12
	s_nop 0
	v_writelane_b32 v237, s0, 47
	s_nop 1
	v_writelane_b32 v237, s1, 48
	v_cmp_ge_u32_e64 s[0:1], v10, v203
	s_nop 1
	v_writelane_b32 v237, s0, 49
	s_nop 1
	v_writelane_b32 v237, s1, 50
	v_cmp_le_u32_e64 s[0:1], v10, v203
	v_or_b32_e32 v10, 0x60, v12
	s_nop 0
	v_writelane_b32 v237, s0, 51
	s_nop 1
	v_writelane_b32 v237, s1, 52
	s_cselect_b64 s[0:1], -1, 0
	s_cmp_lg_u32 s6, 3
	v_cmp_ge_u32_e64 s[6:7], v10, v203
	s_cselect_b64 s[96:97], -1, 0
	s_nop 0
	v_writelane_b32 v237, s6, 53
	s_nop 1
	v_writelane_b32 v237, s7, 54
	v_cmp_le_u32_e64 s[6:7], v10, v203
	v_or_b32_e32 v10, 0x61, v12
	s_nop 0
	v_writelane_b32 v237, s6, 55
	s_nop 1
	v_writelane_b32 v237, s7, 56
	v_cmp_ge_u32_e64 s[6:7], v10, v203
	s_nop 1
	v_writelane_b32 v237, s6, 57
	s_nop 1
	v_writelane_b32 v237, s7, 58
	v_cmp_le_u32_e64 s[6:7], v10, v203
	v_or_b32_e32 v10, 0x62, v12
	s_nop 0
	v_writelane_b32 v237, s6, 59
	s_nop 1
	v_writelane_b32 v237, s7, 60
	v_cmp_ge_u32_e64 s[6:7], v10, v203
	s_nop 1
	v_writelane_b32 v237, s6, 61
	s_nop 1
	v_writelane_b32 v237, s7, 62
	v_cmp_le_u32_e64 s[6:7], v10, v203
	v_or_b32_e32 v10, 0x63, v12
	s_nop 0
	v_writelane_b32 v237, s6, 63
	s_nop 1
	v_writelane_b32 v238, s7, 0
	v_cmp_ge_u32_e64 s[6:7], v10, v203
	s_nop 1
	v_writelane_b32 v238, s6, 1
	s_nop 1
	v_writelane_b32 v238, s7, 2
	v_cmp_le_u32_e64 s[6:7], v10, v203
	v_or_b32_e32 v10, 17, v12
	v_cmp_ge_u32_e64 s[22:23], v10, v205
	v_writelane_b32 v238, s6, 3
	s_nop 1
	v_writelane_b32 v238, s7, 4
	v_writelane_b32 v238, s22, 5
	s_or_b32 s6, s15, 1
	s_cmp_lt_u32 s6, 3
	v_writelane_b32 v238, s23, 6
	v_cmp_le_u32_e64 s[22:23], v10, v205
	v_or_b32_e32 v10, 18, v12
	s_nop 0
	v_writelane_b32 v238, s22, 7
	s_nop 1
	v_writelane_b32 v238, s23, 8
	v_cmp_ge_u32_e64 s[22:23], v10, v205
	s_nop 1
; #define LAS __attribute__((address_space(3)))
; DEV void attn_item(const Fr& F, int l, int b, int qb, int kvh, bool ctxq) {
;     ...
;             const int tl = r0 + mt * 16 + fr;
;             float mx = -INFINITY;
; #pragma unroll
;             for (int nt = 0; nt < 8; ++nt) { if (nt >= nlo && nt < nhi) {
;                 const bool dg = (kt == 2 || kt == 4) && (nt == 2 * rq + mt);
;                 if (dg) {
; #pragma unroll
;                     for (int j = 0; j < 4; ++j) { const int si = nt * 16 + 4 * fq + j; const bool ok = (kt == 2) ? (si >= tl) : (si <= tl); sc[mt][nt][j] = ok ? sc[mt][nt][j] : -INFINITY; } }
;                 else if ((kt == 2 && nt < 2 * rq + mt) || (kt == 4 && nt > 2 * rq + mt)) sc[mt][nt] = (f32x4){-INFINITY, -INFINITY, -INFINITY, -INFINITY};
; __global__ void __launch_bounds__(NTHR, 2) fwd_megakernel(Args args) {
;     ...
;         { unsigned* qctr = (unsigned*)(F.ws + WS_BAR) + XCD_BAR_WORDS + 16 * l; volatile LAS unsigned* qs = (volatile LAS unsigned*)(F.lds + 131072 + 64);
;           for (;;) { __syncthreads(); if (F.tid == 0) qs[0] = atomicAdd(qctr, 1u); __syncthreads(); const int it = (int)qs[0]; if (it >= 512 + 384) break;
	v_writelane_b32 v238, s22, 9
	s_nop 1
	v_writelane_b32 v238, s23, 10
	v_cmp_le_u32_e64 s[22:23], v10, v205
	v_or_b32_e32 v10, 19, v12
	s_nop 0
	v_writelane_b32 v238, s22, 11
	s_nop 1
	v_writelane_b32 v238, s23, 12
	v_cmp_ge_u32_e64 s[22:23], v10, v205
	s_nop 1
	v_writelane_b32 v238, s22, 13
	s_nop 1
	v_writelane_b32 v238, s23, 14
	v_cmp_le_u32_e64 s[22:23], v10, v205
	v_or_b32_e32 v10, 48, v12
	s_nop 0
	v_writelane_b32 v238, s22, 15
	s_nop 1
	v_writelane_b32 v238, s23, 16
	v_cmp_ge_u32_e64 s[22:23], v10, v205
	s_nop 1
	v_writelane_b32 v238, s22, 17
	s_nop 1
	v_writelane_b32 v238, s23, 18
	v_cmp_le_u32_e64 s[22:23], v10, v205
	v_or_b32_e32 v10, 49, v12
	s_nop 0
	v_writelane_b32 v238, s22, 19
	s_nop 1
	v_writelane_b32 v238, s23, 20
	v_cmp_ge_u32_e64 s[22:23], v10, v205
	s_nop 1
	v_writelane_b32 v238, s22, 21
	s_nop 1
	v_writelane_b32 v238, s23, 22
	v_cmp_le_u32_e64 s[22:23], v10, v205
	v_or_b32_e32 v10, 50, v12
	s_nop 0
	v_writelane_b32 v238, s22, 23
	s_nop 1
	v_writelane_b32 v238, s23, 24
	v_cmp_ge_u32_e64 s[22:23], v10, v205
	s_nop 1
	v_writelane_b32 v238, s22, 25
	s_nop 1
	v_writelane_b32 v238, s23, 26
	v_cmp_le_u32_e64 s[22:23], v10, v205
	v_or_b32_e32 v10, 51, v12
	s_nop 0
	v_writelane_b32 v238, s22, 27
	s_nop 1
	v_writelane_b32 v238, s23, 28
	v_cmp_ge_u32_e64 s[22:23], v10, v205
	s_nop 1
	v_writelane_b32 v238, s22, 29
	s_nop 1
	v_writelane_b32 v238, s23, 30
	v_cmp_le_u32_e64 s[22:23], v10, v205
	v_or_b32_e32 v10, 0x50, v12
	s_nop 0
	v_writelane_b32 v238, s22, 31
	s_nop 1
	v_writelane_b32 v238, s23, 32
	s_cselect_b64 s[22:23], -1, 0
	v_writelane_b32 v238, s22, 33
	s_cmp_lt_u32 s6, 5
	v_readlane_b32 s6, v239, 23
	v_writelane_b32 v238, s23, 34
	v_cmp_ge_u32_e64 s[22:23], v10, v205
	v_readlane_b32 s7, v239, 24
	s_cselect_b64 s[42:43], -1, 0
	v_writelane_b32 v238, s22, 35
	v_lshl_add_u64 v[166:167], s[6:7], 0, v[14:15]
	s_add_i32 s6, 0, 0x800
	v_writelane_b32 v238, s23, 36
	v_cmp_le_u32_e64 s[22:23], v10, v205
	v_or_b32_e32 v10, 0x51, v12
	v_add_u32_e32 v209, s6, v5
	v_writelane_b32 v238, s22, 37
	s_nop 1
	v_writelane_b32 v238, s23, 38
	v_cmp_ge_u32_e64 s[22:23], v10, v205
	s_nop 1
	v_writelane_b32 v238, s22, 39
	s_nop 1
	v_writelane_b32 v238, s23, 40
	v_cmp_le_u32_e64 s[22:23], v10, v205
	v_or_b32_e32 v10, 0x52, v12
	s_nop 0
	v_writelane_b32 v238, s22, 41
	s_nop 1
	v_writelane_b32 v238, s23, 42
	v_cmp_ge_u32_e64 s[22:23], v10, v205
	s_nop 1
	v_writelane_b32 v238, s22, 43
	s_nop 1
	v_writelane_b32 v238, s23, 44
	v_cmp_le_u32_e64 s[22:23], v10, v205
	v_or_b32_e32 v10, 0x53, v12
	v_cmp_ge_u32_e64 s[24:25], v10, v205
	v_cmp_le_u32_e64 s[26:27], v10, v205
	v_or_b32_e32 v10, 0x70, v12
	v_cmp_ge_u32_e64 s[28:29], v10, v205
	v_cmp_le_u32_e64 s[30:31], v10, v205
	v_or_b32_e32 v10, 0x71, v12
	v_cmp_ge_u32_e64 s[34:35], v10, v205
	v_cmp_le_u32_e64 s[68:69], v10, v205
	v_or_b32_e32 v10, 0x72, v12
	v_cmp_ge_u32_e64 s[70:71], v10, v205
	v_cmp_le_u32_e64 s[72:73], v10, v205
	v_or_b32_e32 v10, 0x73, v12
	v_cmp_ge_u32_e64 s[74:75], v10, v205
	v_cmp_le_u32_e64 s[76:77], v10, v205
	v_writelane_b32 v238, s38, 45
	v_cndmask_b32_e64 v10, -16, 16, s[48:49]
	v_lshlrev_b64 v[178:179], 1, v[10:11]
	v_writelane_b32 v238, s39, 46
	v_lshl_add_u64 v[164:165], s[38:39], 0, v[20:21]
	v_writelane_b32 v238, s6, 47
	s_mov_b64 s[100:101], exec
	v_readlane_b32 s38, v239, 57
	v_readlane_b32 s39, v239, 58
	s_nop 0
	s_and_b64 s[38:39], s[100:101], s[38:39]
	s_mov_b64 exec, s[38:39]
	s_cbranch_execz .Lqpf_first
	v_mov_b32_e32 v235, 1
	v_readlane_b32 s38, v239, 52
	v_readlane_b32 s39, v239, 53
	s_nop 4
	global_atomic_add v234, v0, v235, s[38:39] sc0
.Lqpf_first:
	s_mov_b64 exec, s[100:101]
	s_branch .LBB0_476

; #define LAS __attribute__((address_space(3)))
; DEV void pool_prefetch(const Fr& F, int it, PoolPre& P) {
;     const int b = it / 520, ch = (it >> 2) % NCH, g = it & 3; const int tid = F.tid;
;     const bool isctx = ch < 2; const int seqlen = isctx ? CTXL : SEQ; const int p0 = isctx ? ch * 128 : (ch - 2) * 128; const int seqrow0 = b * RPB + (isctx ? 0 : CTXL);
; #pragma unroll
;     for (int i = 0; i < 3; ++i) { const int idx = tid + NTHR * i; const int rr = idx >> 3, c8 = (idx & 7) * 8; const int p = p0 - 8 + rr; P.r[i] = (u32x4){0u, 0u, 0u, 0u};
;         if (idx < 144 * 8 && p >= 0 && p < seqlen) P.r[i] = *(const u32x4*)(F.Z + (size_t)(seqrow0 + p) * ZS + ZC_POOL + g * 64 + c8); }
; __global__ void __launch_bounds__(NTHR, 2) fwd_megakernel(Args args) {
;     ...
;         { unsigned* qctr = (unsigned*)(F.ws + WS_BAR) + XCD_BAR_WORDS + 16 * l; volatile LAS unsigned* qs = (volatile LAS unsigned*)(F.lds + 131072 + 64);
;           for (;;) { __syncthreads(); if (F.tid == 0) qs[0] = atomicAdd(qctr, 1u); __syncthreads(); const int it = (int)qs[0]; if (it >= 512 + 384) break;
;               if (it < 512) attn_item(F, l, it >> 8, (it >> 1) & 127, it & 1, false);
;               else pool_phase(F, l, it - 512, 4096); } }
.LBB0_476:
	s_barrier
	s_mov_b64 s[6:7], exec
	v_readlane_b32 s38, v239, 57
	v_readlane_b32 s39, v239, 58
	s_and_b64 s[38:39], s[6:7], s[38:39]
	s_mov_b64 exec, s[38:39]
	s_cbranch_execz .LBB0_480
	s_waitcnt vmcnt(0)
	v_readlane_b32 s38, v240, 55
	s_nop 1
	v_mov_b32_e32 v2, s38
	ds_write_b32 v2, v234
.LBB0_480:
	s_or_b64 exec, exec, s[6:7]
	v_readlane_b32 s6, v240, 55
	s_waitcnt lgkmcnt(0)
	s_barrier
	v_mov_b32_e32 v1, s6
	ds_read_b32 v1, v1
	s_mov_b64 s[6:7], -1
	s_waitcnt lgkmcnt(0)
	v_readfirstlane_b32 s40, v1
	s_cmpk_gt_i32 s40, 0x37f
	s_cbranch_scc1 .LBB0_475
	s_mov_b64 s[100:101], exec
	v_readlane_b32 s38, v239, 57
	v_readlane_b32 s39, v239, 58
	s_nop 0
	s_and_b64 s[38:39], s[100:101], s[38:39]
	s_mov_b64 exec, s[38:39]
	s_cbranch_execz .Lqpf_next
	v_mov_b32_e32 v235, 1
	v_readlane_b32 s38, v239, 52
	v_readlane_b32 s39, v239, 53
	s_nop 4
	global_atomic_add v234, v0, v235, s[38:39] sc0
.Lqpf_next:
	s_mov_b64 exec, s[100:101]
	s_cmpk_gt_i32 s40, 0x1ff
	s_cbranch_scc0 .LBB0_498
	s_add_i32 s38, s40, 0xfffffe00
	s_cmp_lt_u32 s38, 8
	s_cselect_b64 s[6:7], -1, 0
	s_add_i32 s39, s40, 0xe00
	s_and_b64 s[6:7], s[8:9], s[6:7]
	s_and_b64 s[6:7], s[6:7], exec
	s_cselect_b32 s41, s39, s38
	s_mov_b64 s[38:39], 0
	s_cmpk_lt_u32 s41, 0x410
	s_mov_b64 s[6:7], 0
	s_cbranch_scc0 .LBB0_499
	s_lshr_b32 s6, s41, 2
	s_add_i32 s7, s6, 0xffffff7e
	s_cmpk_lt_u32 s41, 0x208
	s_cselect_b32 s6, s6, s7
	s_lshl_b32 s44, s6, 7
	s_add_i32 s7, s44, 0xffffff00
	s_cmp_lt_u32 s6, 2
	s_movk_i32 s6, 0x4000
	s_cselect_b32 s56, 0x100, s6
	s_cselect_b32 s58, 0, 0x100
	s_cselect_b32 s57, s44, s7
	s_cmpk_gt_u32 s41, 0x207
	s_cselect_b32 s45, 0x4100, 0
	s_add_i32 s62, s57, -8
	s_lshl_b32 s6, s41, 6
	s_and_b32 s59, s6, 0xc0
	v_add_u32_e32 v1, s62, v141
	v_readlane_b32 s6, v239, 59
	v_cmp_gt_u32_e32 vcc, s56, v1
	v_readlane_b32 s7, v239, 60
	s_add_i32 s58, s58, s45
	s_and_b64 s[64:65], s[6:7], vcc
	v_mov_b32_e32 v2, 0
	v_mov_b32_e32 v6, 0
	v_mov_b32_e32 v7, 0
	v_mov_b32_e32 v8, 0
	v_mov_b32_e32 v9, 0
	s_and_saveexec_b64 s[6:7], s[64:65]
	s_cbranch_execz .LBB0_485
	v_readlane_b32 s64, v239, 23
	v_readlane_b32 s65, v239, 24
	v_add_u32_e32 v1, s58, v1
	s_lshl_b32 s60, s59, 1
	v_mov_b64_e32 v[4:5], s[64:65]
	v_mad_u64_u32 v[4:5], s[64:65], v1, s66, v[4:5]
	v_lshl_add_u64 v[4:5], v[4:5], 0, s[60:61]
	v_lshlrev_b32_e32 v6, 1, v150
	v_mov_b32_e32 v7, v0
	v_lshl_add_u64 v[4:5], v[4:5], 0, v[6:7]
	v_add_co_u32_e32 v4, vcc, 0x1000, v4
	s_nop 1
	v_addc_co_u32_e32 v5, vcc, 0, v5, vcc
	global_load_dwordx4 v[6:9], v[4:5], off offset:32
